# MLA attention loop: K/V LDS-DMA addresses as SGPR base (readfirstlane of the uniform K/V pointers, SALU row offsets) + 32-bit lane offset instead of 64-bit VALU adds and v_mad_u64
# baseline (speedup 1.0000x reference)
.LBB0_2190:
	v_and_b32_e32 v50, 63, v192
	v_lshlrev_b32_e32 v52, 4, v50
	v_lshlrev_b32_e32 v51, 3, v50
	v_and_b32_e32 v52, 0xc0, v52
	v_lshlrev_b32_e32 v53, 1, v50
	v_and_or_b32 v52, v51, 24, v52
	v_and_b32_e32 v53, 32, v53
	v_and_b32_e32 v51, 0x100, v51
	v_or3_b32 v51, v52, v53, v51
	v_add_u32_e32 v209, 0, v51
	v_max_f32_e32 v51, v35, v35
	v_max_f32_e32 v52, v34, v34
	v_max_f32_e32 v51, v52, v51
	v_max3_f32 v51, v51, v36, v37
	v_max3_f32 v51, v51, v38, v39
	v_max3_f32 v51, v51, v40, v41
	v_max3_f32 v51, v51, v42, v43
	v_max3_f32 v51, v51, v44, v45
	v_max3_f32 v51, v51, v46, v47
	v_max3_f32 v51, v51, v48, v49
	v_max3_f32 v51, v51, v18, v19
	v_max3_f32 v51, v51, v20, v21
	v_max3_f32 v51, v51, v22, v23
	v_max3_f32 v51, v51, v24, v25
	v_max3_f32 v51, v51, v26, v27
	v_max3_f32 v51, v51, v28, v29
	v_max3_f32 v51, v51, v30, v31
	v_max3_f32 v51, v51, v32, v33
	v_mov_b32_e32 v52, v51
	s_nop 1
	v_permlane32_swap_b32_e32 v51, v52
	v_max_f32_e32 v52, v52, v52
	v_max_f32_e32 v51, v51, v51
	s_lshl_b32 s1, s1, 8
	v_max_f32_e32 v51, v51, v52
	s_lshl_b32 s0, s0, 2
	s_add_i32 s10, s1, 0
	v_add_f32_e32 v52, 0x7149f2ca, v51
	s_sub_i32 s21, 0x100, s0
	s_add_i32 s10, s10, 0x18000
	s_add_i32 s11, s11, -2.0
	v_cmp_ge_f32_e32 vcc, s83, v52
	v_max_f32_e32 v51, 0xf149f2ca, v51
	s_cmp_eq_u64 vcc, exec
	v_sub_f32_e32 v53, 0xf149f2ca, v51
	s_cselect_b64 vcc, -1, 0
	v_exp_f32_e32 v53, v53
	v_cndmask_b32_e32 v238, v51, v199, vcc
	v_sub_f32_e32 v34, v34, v238
	v_sub_f32_e32 v35, v35, v238
	v_sub_f32_e32 v36, v36, v238
	v_sub_f32_e32 v37, v37, v238
	v_sub_f32_e32 v38, v38, v238
	v_sub_f32_e32 v39, v39, v238
	v_sub_f32_e32 v40, v40, v238
	v_sub_f32_e32 v41, v41, v238
	v_sub_f32_e32 v42, v42, v238
	v_sub_f32_e32 v43, v43, v238
	v_sub_f32_e32 v44, v44, v238
	v_sub_f32_e32 v45, v45, v238
	v_sub_f32_e32 v46, v46, v238
	v_sub_f32_e32 v47, v47, v238
	v_sub_f32_e32 v48, v48, v238
	v_sub_f32_e32 v49, v49, v238
	v_exp_f32_e32 v82, v34
	v_exp_f32_e32 v83, v35
	v_exp_f32_e32 v84, v36
	v_exp_f32_e32 v85, v37
	v_exp_f32_e32 v86, v38
	v_exp_f32_e32 v87, v39
	v_exp_f32_e32 v88, v40
	v_exp_f32_e32 v89, v41
	v_exp_f32_e32 v90, v42
	v_exp_f32_e32 v91, v43
	v_exp_f32_e32 v92, v44
	v_exp_f32_e32 v93, v45
	v_exp_f32_e32 v94, v46
	v_exp_f32_e32 v95, v47
	v_exp_f32_e32 v96, v48
	v_exp_f32_e32 v97, v49
	s_add_i32 s2, s6, 0x3e45
	v_sub_f32_e32 v98, v18, v238
	s_waitcnt vmcnt(0)
	s_sub_i32 s22, 0xff, s0
	v_cmp_gt_u32_e64 s[0:1], 32, v50
	v_add_u32_e32 v18, s2, v14
	v_mov_b32_e32 v50, v1
	v_mov_b32_e32 v51, v1
	v_mov_b32_e32 v64, v1
	v_mov_b32_e32 v65, v1
	v_cndmask_b32_e64 v236, v53, 1.0, vcc
	v_sub_f32_e32 v113, v33, v238
	v_sub_f32_e32 v112, v32, v238
	v_sub_f32_e32 v111, v31, v238
	v_sub_f32_e32 v110, v30, v238
	v_sub_f32_e32 v109, v29, v238
	v_sub_f32_e32 v108, v28, v238
	v_sub_f32_e32 v107, v27, v238
	v_sub_f32_e32 v106, v26, v238
	v_sub_f32_e32 v105, v25, v238
	v_sub_f32_e32 v104, v24, v238
	v_sub_f32_e32 v103, v23, v238
	v_sub_f32_e32 v102, v22, v238
	v_sub_f32_e32 v101, v21, v238
	v_sub_f32_e32 v100, v20, v238
	v_sub_f32_e32 v99, v19, v238
	v_lshl_add_u32 v227, v17, 2, s10
	v_sub_u32_e32 v17, v18, v17
	v_mov_b32_e32 v52, v1
	v_mov_b32_e32 v53, v1
	v_mov_b32_e32 v54, v1
	v_mov_b32_e32 v55, v1
	v_mov_b32_e32 v56, v1
	v_mov_b32_e32 v57, v1
	v_mov_b32_e32 v58, v1
	v_mov_b32_e32 v59, v1
	v_mov_b32_e32 v60, v1
	v_mov_b32_e32 v61, v1
	v_mov_b32_e32 v62, v1
	v_mov_b32_e32 v63, v1
	v_mov_b64_e32 v[80:81], v[64:65]
	v_mov_b64_e32 v[34:35], v[50:51]
	v_mov_b64_e32 v[18:19], v[50:51]
	v_mov_b32_e32 v211, v1
	v_mov_b32_e32 v213, v1
	v_mov_b32_e32 v215, v1
	v_mov_b32_e32 v217, v1
	s_mov_b32 s20, 2
	v_lshl_add_u32 v228, v14, 2, s10
	v_subrev_u32_e32 v237, s8, v17
	s_mov_b32 s26, 0
	v_mov_b32_e32 v17, 0
	s_movk_i32 s23, 0xbf
	v_mov_b64_e32 v[78:79], v[62:63]
	v_mov_b64_e32 v[76:77], v[60:61]
	v_mov_b64_e32 v[74:75], v[58:59]
	v_mov_b64_e32 v[72:73], v[56:57]
	v_mov_b64_e32 v[70:71], v[54:55]
	v_mov_b64_e32 v[68:69], v[52:53]
	v_mov_b64_e32 v[66:67], v[50:51]
	v_mov_b64_e32 v[36:37], v[52:53]
	v_mov_b64_e32 v[38:39], v[54:55]
	v_mov_b64_e32 v[40:41], v[56:57]
	v_mov_b64_e32 v[42:43], v[58:59]
	v_mov_b64_e32 v[44:45], v[60:61]
	v_mov_b64_e32 v[46:47], v[62:63]
	v_mov_b64_e32 v[48:49], v[64:65]
	v_mov_b64_e32 v[20:21], v[52:53]
	v_mov_b64_e32 v[22:23], v[54:55]
	v_mov_b64_e32 v[24:25], v[56:57]
	v_mov_b64_e32 v[26:27], v[58:59]
	v_mov_b64_e32 v[28:29], v[60:61]
	v_mov_b64_e32 v[30:31], v[62:63]
	v_mov_b64_e32 v[32:33], v[64:65]
	v_readfirstlane_b32 s60, v204
	v_readfirstlane_b32 s61, v205
	v_readfirstlane_b32 s62, v206
	v_readfirstlane_b32 s63, v207
	s_waitcnt vmcnt(0) lgkmcnt(0)
	s_barrier
.LBB0_2191:
	v_mov_b32_e32 v114, v14
	s_add_i32 s24, 0, 0x12000
	v_mul_lo_u32 v115, v114, s84
	v_lshlrev_b32_e32 v114, 3, v114
	v_add_u32_e32 v115, s24, v115
	v_and_b32_e32 v114, 0x70, v114
	v_xad_u32 v242, v114, v208, v115
	v_xad_u32 v241, v114, v229, v115
	v_xad_u32 v240, v114, v234, v115
	v_xad_u32 v239, v114, v235, v115
	ds_read_b128 v[114:117], v242 offset:0
	ds_read_b128 v[130:133], v242 offset:0x3000
	ds_read_b128 v[194:197], v241 offset:0
	v_exp_f32_e32 v98, v98
	ds_read_b128 v[186:189], v241 offset:0x3000
	s_waitcnt lgkmcnt(3)
	v_add_f32_e32 v134, 0, v82
	v_mfma_f32_32x32x16_bf16 v[114:129], v[114:117], v[178:181], 0
	ds_read_b128 v[182:185], v240 offset:0
	v_add_f32_e32 v190, 0, v98
	s_waitcnt lgkmcnt(3)
	s_sub_i32 s25, s23, 63
	v_exp_f32_e32 v99, v99
	v_add_f32_e32 v202, v134, v83
	v_mfma_f32_32x32x16_bf16 v[130:145], v[130:133], v[178:181], 0
	s_mul_hi_u32 s3, s25, 0x900
	v_add_f32_e32 v243, v190, v99
	ds_read_b128 v[190:193], v240 offset:0x3000
	s_mul_i32 s2, s25, 0x900
	s_add_u32 s64, s60, s2
	s_addc_u32 s65, s61, s3
	v_exp_f32_e32 v100, v100
	s_mov_b32 m0, s13
	s_nop 0
	global_load_lds_dwordx4 v0, s[64:65]
	s_waitcnt lgkmcnt(3)
	v_add_f32_e32 v244, v202, v84
	v_mfma_f32_32x32x16_bf16 v[114:129], v[194:197], v[174:177], v[114:129]
	v_add_f32_e32 v200, v243, v100
	ds_read_b128 v[194:197], v239 offset:0
	s_waitcnt lgkmcnt(3)
	s_mov_b32 m0, s14
	v_exp_f32_e32 v101, v101
	v_mfma_f32_32x32x16_bf16 v[130:145], v[186:189], v[174:177], v[130:145]
	v_add_f32_e32 v201, v244, v85
	ds_read_b128 v[186:189], v239 offset:0x3000
	v_add_f32_e32 v200, v200, v101
	s_waitcnt lgkmcnt(3)
	v_exp_f32_e32 v102, v102
	v_mfma_f32_32x32x16_bf16 v[114:129], v[182:185], v[170:173], v[114:129]
	v_add_f32_e32 v201, v201, v86
	ds_read_b128 v[182:185], v242 offset:0x80
	v_add_f32_e32 v200, v200, v102
	s_waitcnt lgkmcnt(3)
	s_mul_hi_u32 s3, s25, 0x600
	v_exp_f32_e32 v103, v103
	v_mfma_f32_32x32x16_bf16 v[130:145], v[190:193], v[170:173], v[130:145]
	v_add_f32_e32 v201, v201, v87
	ds_read_b128 v[190:193], v242 offset:0x3080
	v_add_f32_e32 v200, v200, v103
	global_load_lds_dwordx4 v210, s[64:65]
	v_exp_f32_e32 v104, v104
	s_waitcnt lgkmcnt(3)
	v_add_f32_e32 v201, v201, v88
	v_mfma_f32_32x32x16_bf16 v[114:129], v[194:197], v[166:169], v[114:129]
	v_add_f32_e32 v200, v200, v104
	ds_read_b128 v[194:197], v241 offset:0x80
	s_mov_b32 m0, s15
	s_waitcnt lgkmcnt(3)
	s_mul_i32 s2, s25, 0x600
	v_exp_f32_e32 v105, v105
	v_mfma_f32_32x32x16_bf16 v[130:145], v[186:189], v[166:169], v[130:145]
	v_add_f32_e32 v201, v201, v89
	ds_read_b128 v[186:189], v241 offset:0x3080
	v_add_f32_e32 v200, v200, v105
	s_waitcnt lgkmcnt(3)
	s_add_u32 s66, s62, s2
	s_addc_u32 s67, s63, s3
	v_exp_f32_e32 v106, v106
	v_mfma_f32_32x32x16_bf16 v[114:129], v[182:185], v[162:165], v[114:129]
	v_add_f32_e32 v201, v201, v90
	ds_read_b128 v[182:185], v240 offset:0x80
	v_add_f32_e32 v200, v200, v106
	s_waitcnt lgkmcnt(3)
	s_lshl_b32 s2, s26, 14
	v_exp_f32_e32 v107, v107
	v_mfma_f32_32x32x16_bf16 v[130:145], v[190:193], v[162:165], v[130:145]
	v_add_f32_e32 v201, v201, v91
	ds_read_b128 v[190:193], v240 offset:0x3080
	v_add_f32_e32 v200, v200, v107
	s_waitcnt lgkmcnt(3)
	s_add_i32 s3, s2, 0xffffc000
	v_exp_f32_e32 v108, v108
	v_mfma_f32_32x32x16_bf16 v[114:129], v[194:197], v[158:161], v[114:129]
	v_add_f32_e32 v222, v201, v92
	s_cmp_lg_u32 s26, 0
	v_add_f32_e32 v194, v200, v108
	ds_read_b128 v[200:203], v239 offset:0x80
	s_cselect_b32 s3, s3, 0x8000
	global_load_lds_dwordx4 v212, s[64:65]
	v_exp_f32_e32 v109, v109
	s_waitcnt lgkmcnt(3)
	v_add_f32_e32 v195, v222, v93
	v_mfma_f32_32x32x16_bf16 v[130:145], v[186:189], v[158:161], v[130:145]
	v_add_f32_e32 v186, v194, v109
	ds_read_b128 v[230:233], v239 offset:0x3080
	s_add_i32 s3, s12, s3
	s_waitcnt lgkmcnt(3)
	v_exp_f32_e32 v110, v110
	v_mfma_f32_32x32x16_bf16 v[114:129], v[182:185], v[154:157], v[114:129]
	v_add_f32_e32 v187, v195, v94
	ds_read_b128 v[182:185], v242 offset:0x100
	v_add_f32_e32 v186, v186, v110
	s_waitcnt lgkmcnt(3)
	s_mov_b32 m0, s3
	v_exp_f32_e32 v111, v111
	v_mfma_f32_32x32x16_bf16 v[130:145], v[190:193], v[154:157], v[130:145]
	v_add_f32_e32 v187, v187, v95
	ds_read_b128 v[194:197], v242 offset:0x3100
	v_add_f32_e32 v186, v186, v111
	s_waitcnt lgkmcnt(3)
	v_exp_f32_e32 v112, v112
	v_mfma_f32_32x32x16_bf16 v[114:129], v[200:203], v[150:153], v[114:129]
	v_add_f32_e32 v190, v187, v96
	s_sub_i32 s27, s23, 64
	v_add_f32_e32 v191, v186, v112
	ds_read_b128 v[186:189], v241 offset:0x100
	s_waitcnt lgkmcnt(3)
	v_exp_f32_e32 v113, v113
	v_mfma_f32_32x32x16_bf16 v[130:145], v[230:233], v[150:153], v[130:145]
	v_add_f32_e32 v222, v190, v97
	v_add_f32_e32 v223, v191, v113
	ds_read_b128 v[190:193], v241 offset:0x3100
	global_load_lds_dwordx4 v214, s[66:67]
	s_waitcnt lgkmcnt(3)
	s_add_i32 m0, s3, 0x2000
	v_mfma_f32_32x32x16_bf16 v[114:129], v[182:185], v[146:149], v[114:129]
	ds_read_b128 v[200:203], v240 offset:0x100
	v_cvt_pk_bf16_f32 v182, v82, v83
	v_cvt_pk_bf16_f32 v184, v86, v87
	s_add_i32 s3, s23, 0xffffff81
	v_permlane32_swap_b32_e32 v182, v184
	s_waitcnt lgkmcnt(3)
	s_cmp_le_i32 s27, s9
	v_mfma_f32_32x32x16_bf16 v[130:145], v[194:197], v[146:149], v[130:145]
	ds_read_b128 v[194:197], v240 offset:0x3100
	v_cvt_pk_bf16_f32 v183, v84, v85
	v_cvt_pk_bf16_f32 v185, v88, v89
	s_cselect_b64 s[28:29], -1, 0
	v_permlane32_swap_b32_e32 v183, v185
	s_waitcnt lgkmcnt(3)
	s_cmp_gt_i32 s3, s11
	v_mfma_f32_32x32x16_bf16 v[114:129], v[186:189], v[10:13], v[114:129]
	ds_read_b128 v[230:233], v239 offset:0x100
	v_cvt_pk_bf16_f32 v186, v90, v91
	v_cvt_pk_bf16_f32 v188, v94, v95
	s_cselect_b64 s[30:31], -1, 0
	v_permlane32_swap_b32_e32 v186, v188
	s_waitcnt lgkmcnt(3)
	s_and_b64 s[28:29], s[28:29], s[30:31]
	v_mfma_f32_32x32x16_bf16 v[130:145], v[190:193], v[10:13], v[130:145]
	ds_read_b128 v[218:221], v239 offset:0x3100
	v_cvt_pk_bf16_f32 v187, v92, v93
	v_cvt_pk_bf16_f32 v189, v96, v97
	s_and_b64 vcc, exec, s[28:29]
	v_permlane32_swap_b32_e32 v187, v189
	s_waitcnt lgkmcnt(3)
	v_cvt_pk_bf16_f32 v190, v98, v99
	v_cvt_pk_bf16_f32 v192, v102, v103
	v_mfma_f32_32x32x16_bf16 v[114:129], v[200:203], v[6:9], v[114:129]
	v_permlane32_swap_b32_e32 v190, v192
	global_load_lds_dwordx4 v216, s[66:67]
	s_waitcnt lgkmcnt(2)
	v_cvt_pk_bf16_f32 v191, v100, v101
	v_cvt_pk_bf16_f32 v193, v104, v105
	s_nop 0
	v_mfma_f32_32x32x16_bf16 v[130:145], v[194:197], v[6:9], v[130:145]
	v_permlane32_swap_b32_e32 v191, v193
	s_waitcnt lgkmcnt(1)
	v_cvt_pk_bf16_f32 v194, v106, v107
	v_cvt_pk_bf16_f32 v196, v110, v111
	v_mfma_f32_32x32x16_bf16 v[114:129], v[230:233], v[2:5], v[114:129]
	v_permlane32_swap_b32_e32 v194, v196
	s_waitcnt lgkmcnt(0)
	v_cvt_pk_bf16_f32 v195, v108, v109
	v_cvt_pk_bf16_f32 v197, v112, v113
	v_mfma_f32_32x32x16_bf16 v[130:145], v[218:221], v[2:5], v[130:145]
	v_permlane32_swap_b32_e32 v195, v197
	v_add_f32_e32 v222, v222, v223
	v_mov_b32_e32 v223, v222
	s_nop 1
	v_permlane32_swap_b32_e32 v222, v223
	s_cbranch_vccnz .LBB0_2193
	v_add_u32_e32 v82, 0x7b, v237
	v_cmp_gt_u32_e32 vcc, 2.0, v82
	v_add_u32_e32 v82, 0x5b, v237
	s_nop 0
	v_cndmask_b32_e32 v114, v16, v114, vcc
	v_cmp_gt_u32_e32 vcc, 2.0, v82
	v_add_u32_e32 v82, 0x7a, v237
	s_nop 0
	v_cndmask_b32_e32 v130, v16, v130, vcc
	v_cmp_gt_u32_e32 vcc, 2.0, v82
	v_add_u32_e32 v82, 0x5a, v237
	s_nop 0
	v_cndmask_b32_e32 v115, v16, v115, vcc
	v_cmp_gt_u32_e32 vcc, 2.0, v82
	v_add_u32_e32 v82, 0x79, v237
	s_nop 0
	v_cndmask_b32_e32 v131, v16, v131, vcc
	v_cmp_gt_u32_e32 vcc, 2.0, v82
	v_add_u32_e32 v82, 0x59, v237
	s_nop 0
	v_cndmask_b32_e32 v116, v16, v116, vcc
	v_cmp_gt_u32_e32 vcc, 2.0, v82
	v_add_u32_e32 v82, 0x78, v237
	s_nop 0
	v_cndmask_b32_e32 v132, v16, v132, vcc
	v_cmp_gt_u32_e32 vcc, 2.0, v82
	v_add_u32_e32 v82, 0x58, v237
	s_nop 0
	v_cndmask_b32_e32 v117, v16, v117, vcc
	v_cmp_gt_u32_e32 vcc, 2.0, v82
	v_add_u32_e32 v82, 0x73, v237
	s_nop 0
	v_cndmask_b32_e32 v133, v16, v133, vcc
	v_cmp_gt_u32_e32 vcc, 2.0, v82
	v_add_u32_e32 v82, 0x53, v237
	s_nop 0
	v_cndmask_b32_e32 v118, v16, v118, vcc
	v_cmp_gt_u32_e32 vcc, 2.0, v82
	v_add_u32_e32 v82, 0x72, v237
	s_nop 0
	v_cndmask_b32_e32 v134, v16, v134, vcc
	v_cmp_gt_u32_e32 vcc, 2.0, v82
	v_add_u32_e32 v82, 0x52, v237
	s_nop 0
	v_cndmask_b32_e32 v119, v16, v119, vcc
	v_cmp_gt_u32_e32 vcc, 2.0, v82
	v_add_u32_e32 v82, 0x71, v237
	s_nop 0
	v_cndmask_b32_e32 v135, v16, v135, vcc
	v_cmp_gt_u32_e32 vcc, 2.0, v82
	v_add_u32_e32 v82, 0x51, v237
	s_nop 0
	v_cndmask_b32_e32 v120, v16, v120, vcc
	v_cmp_gt_u32_e32 vcc, 2.0, v82
	v_add_u32_e32 v82, 0x70, v237
	s_nop 0
	v_cndmask_b32_e32 v136, v16, v136, vcc
	v_cmp_gt_u32_e32 vcc, 2.0, v82
	v_add_u32_e32 v82, 0x50, v237
	s_nop 0
	v_cndmask_b32_e32 v121, v16, v121, vcc
	v_cmp_gt_u32_e32 vcc, 2.0, v82
	v_add_u32_e32 v82, 0x6b, v237
	s_nop 0
	v_cndmask_b32_e32 v137, v16, v137, vcc
	v_cmp_gt_u32_e32 vcc, 2.0, v82
	v_add_u32_e32 v82, 0x4b, v237
	s_nop 0
	v_cndmask_b32_e32 v122, v16, v122, vcc
	v_cmp_gt_u32_e32 vcc, 2.0, v82
	v_add_u32_e32 v82, 0x6a, v237
	s_nop 0
	v_cndmask_b32_e32 v138, v16, v138, vcc
	v_cmp_gt_u32_e32 vcc, 2.0, v82
	v_add_u32_e32 v82, 0x4a, v237
	s_nop 0
	v_cndmask_b32_e32 v123, v16, v123, vcc
	v_cmp_gt_u32_e32 vcc, 2.0, v82
	v_add_u32_e32 v82, 0x69, v237
	s_nop 0
	v_cndmask_b32_e32 v139, v16, v139, vcc
	v_cmp_gt_u32_e32 vcc, 2.0, v82
	v_add_u32_e32 v82, 0x49, v237
	s_nop 0
	v_cndmask_b32_e32 v124, v16, v124, vcc
	v_cmp_gt_u32_e32 vcc, 2.0, v82
	v_add_u32_e32 v82, 0x68, v237
	s_nop 0
	v_cndmask_b32_e32 v140, v16, v140, vcc
	v_cmp_gt_u32_e32 vcc, 2.0, v82
	v_add_u32_e32 v82, 0x48, v237
	s_nop 0
	v_cndmask_b32_e32 v125, v16, v125, vcc
	v_cmp_gt_u32_e32 vcc, 2.0, v82
	v_add_u32_e32 v82, 0x63, v237
	s_nop 0
	v_cndmask_b32_e32 v141, v16, v141, vcc
	v_cmp_gt_u32_e32 vcc, 2.0, v82
	v_add_u32_e32 v82, 0x43, v237
	s_nop 0
	v_cndmask_b32_e32 v126, v16, v126, vcc
	v_cmp_gt_u32_e32 vcc, 2.0, v82
	v_add_u32_e32 v82, 0x62, v237
	s_nop 0
	v_cndmask_b32_e32 v142, v16, v142, vcc
	v_cmp_gt_u32_e32 vcc, 2.0, v82
	v_add_u32_e32 v82, 0x42, v237
	s_nop 0
	v_cndmask_b32_e32 v127, v16, v127, vcc
	v_cmp_gt_u32_e32 vcc, 2.0, v82
	v_add_u32_e32 v82, 0x61, v237
	s_nop 0
	v_cndmask_b32_e32 v143, v16, v143, vcc
	v_cmp_gt_u32_e32 vcc, 2.0, v82
	v_add_u32_e32 v82, 0x41, v237
	s_nop 0
	v_cndmask_b32_e32 v128, v16, v128, vcc
	v_cmp_gt_u32_e32 vcc, 2.0, v82
	v_add_u32_e32 v82, 0x60, v237
	s_nop 0
	v_cndmask_b32_e32 v144, v16, v144, vcc
	v_cmp_gt_u32_e32 vcc, 2.0, v82
	v_add_u32_e32 v82, 64, v237
	s_nop 0
	v_cndmask_b32_e32 v129, v16, v129, vcc
	v_cmp_gt_u32_e32 vcc, 2.0, v82
	s_nop 1
	v_cndmask_b32_e32 v145, v16, v145, vcc

.LBB0_2197:
	v_mov_b32_e32 v82, v14
	s_waitcnt vmcnt(0)
	s_waitcnt vmcnt(0) lgkmcnt(0)
	s_barrier
	v_exp_f32_e32 v130, v130
	v_mul_lo_u32 v83, v82, s84
	v_lshlrev_b32_e32 v82, 3, v82
	v_add_u32_e32 v83, s19, v83
	v_and_b32_e32 v82, 0x70, v82
	v_xad_u32 v241, v82, v208, v83
	v_xad_u32 v240, v82, v229, v83
	v_xad_u32 v239, v82, v234, v83
	v_xad_u32 v238, v82, v235, v83
	ds_read_b128 v[82:85], v241 offset:0
	ds_read_b128 v[98:101], v241 offset:0x3000
	ds_read_b128 v[200:203], v240 offset:0
	ds_read_b128 v[190:193], v240 offset:0x3000
	v_add_f32_e32 v196, 0, v114
	s_waitcnt lgkmcnt(3)
	v_add_f32_e32 v197, 0, v130
	v_mfma_f32_32x32x16_bf16 v[82:97], v[82:85], v[178:181], 0
	ds_read_b128 v[182:185], v239 offset:0
	s_add_i32 s2, s26, 1
	s_cmp_lg_u32 s26, 2
	v_exp_f32_e32 v131, v131
	s_waitcnt lgkmcnt(3)
	s_cselect_b32 s26, s2, 0
	s_add_i32 s2, s20, 1
	v_mfma_f32_32x32x16_bf16 v[98:113], v[98:101], v[178:181], 0
	s_min_i32 s2, s2, s22
	ds_read_b128 v[186:189], v239 offset:0x3000
	v_add_f32_e32 v220, v196, v115
	v_add_f32_e32 v221, v197, v131
	s_lshl_b32 s27, s2, 6
	s_mul_i32 s68, s27, 0x900
	s_mul_hi_u32 s69, s27, 0x900
	s_add_u32 s68, s68, s60
	s_addc_u32 s69, s69, s61
	v_exp_f32_e32 v132, v132
	s_mov_b32 m0, s16
	s_nop 0
	global_load_lds_dwordx4 v0, s[68:69]
	s_waitcnt lgkmcnt(3)
	v_add_f32_e32 v243, v220, v116
	v_mfma_f32_32x32x16_bf16 v[82:97], v[200:203], v[174:177], v[82:97]
	v_add_f32_e32 v242, v221, v132
	ds_read_b128 v[200:203], v238 offset:0
	s_waitcnt lgkmcnt(3)
	s_mov_b32 m0, s17
	v_exp_f32_e32 v133, v133
	v_mfma_f32_32x32x16_bf16 v[98:113], v[190:193], v[174:177], v[98:113]
	v_add_f32_e32 v230, v243, v117
	ds_read_b128 v[190:193], v238 offset:0x3000
	v_add_f32_e32 v231, v242, v133
	s_waitcnt lgkmcnt(3)
	v_exp_f32_e32 v134, v134
	v_mfma_f32_32x32x16_bf16 v[82:97], v[182:185], v[170:173], v[82:97]
	v_add_f32_e32 v230, v230, v118
	ds_read_b128 v[182:185], v241 offset:0x80
	v_add_f32_e32 v231, v231, v134
	s_waitcnt lgkmcnt(3)
	s_mul_i32 s74, s27, 0x600
	s_mul_hi_u32 s75, s27, 0x600
	s_add_u32 s74, s74, s62
	s_addc_u32 s75, s75, s63
	v_exp_f32_e32 v135, v135
	v_mfma_f32_32x32x16_bf16 v[98:113], v[186:189], v[170:173], v[98:113]
	v_add_f32_e32 v230, v230, v119
	ds_read_b128 v[186:189], v241 offset:0x3080
	v_add_f32_e32 v231, v231, v135
	global_load_lds_dwordx4 v210, s[68:69]
	v_exp_f32_e32 v136, v136
	s_waitcnt lgkmcnt(3)
	v_add_f32_e32 v196, v230, v120
	v_mfma_f32_32x32x16_bf16 v[82:97], v[200:203], v[166:169], v[82:97]
	v_add_f32_e32 v197, v231, v136
	ds_read_b128 v[200:203], v240 offset:0x80
	s_mov_b32 m0, s18
	s_waitcnt lgkmcnt(3)
	s_lshl_b32 s2, s26, 14
	v_exp_f32_e32 v137, v137
	v_mfma_f32_32x32x16_bf16 v[98:113], v[190:193], v[166:169], v[98:113]
	v_add_f32_e32 v196, v196, v121
	ds_read_b128 v[190:193], v240 offset:0x3080
	v_add_f32_e32 v197, v197, v137
	s_waitcnt lgkmcnt(3)
	s_add_i32 s3, s2, 0xffffc000
	v_exp_f32_e32 v138, v138
	v_mfma_f32_32x32x16_bf16 v[82:97], v[182:185], v[162:165], v[82:97]
	v_add_f32_e32 v196, v196, v122
	ds_read_b128 v[182:185], v239 offset:0x80
	v_add_f32_e32 v197, v197, v138
	s_waitcnt lgkmcnt(3)
	s_cmp_lg_u32 s26, 0
	v_exp_f32_e32 v139, v139
	v_mfma_f32_32x32x16_bf16 v[98:113], v[186:189], v[162:165], v[98:113]
	v_add_f32_e32 v196, v196, v123
	ds_read_b128 v[186:189], v239 offset:0x3080
	v_add_f32_e32 v197, v197, v139
	s_waitcnt lgkmcnt(3)
	s_cselect_b32 s3, s3, 0x8000
	v_exp_f32_e32 v140, v140
	v_mfma_f32_32x32x16_bf16 v[82:97], v[200:203], v[158:161], v[82:97]
	v_add_f32_e32 v196, v196, v124
	ds_read_b128 v[200:203], v238 offset:0x80
	v_add_f32_e32 v197, v197, v140
	global_load_lds_dwordx4 v212, s[68:69]
	v_exp_f32_e32 v141, v141
	s_waitcnt lgkmcnt(3)
	v_add_f32_e32 v194, v196, v125
	v_mfma_f32_32x32x16_bf16 v[98:113], v[190:193], v[158:161], v[98:113]
	v_add_f32_e32 v195, v197, v141
	ds_read_b128 v[190:193], v238 offset:0x3080
	s_add_i32 s3, s12, s3
	s_waitcnt lgkmcnt(3)
	v_exp_f32_e32 v142, v142
	v_mfma_f32_32x32x16_bf16 v[82:97], v[182:185], v[154:157], v[82:97]
	v_add_f32_e32 v194, v194, v126
	ds_read_b128 v[182:185], v241 offset:0x100
	v_add_f32_e32 v195, v195, v142
	s_waitcnt lgkmcnt(3)
	s_mov_b32 m0, s3
	v_exp_f32_e32 v143, v143
	v_mfma_f32_32x32x16_bf16 v[98:113], v[186:189], v[154:157], v[98:113]
	v_add_f32_e32 v230, v194, v127
	v_add_f32_e32 v186, v195, v143
	ds_read_b128 v[194:197], v241 offset:0x3100
	s_waitcnt lgkmcnt(3)
	v_exp_f32_e32 v144, v144
	v_mfma_f32_32x32x16_bf16 v[82:97], v[200:203], v[150:153], v[82:97]
	v_add_f32_e32 v230, v230, v128
	v_add_f32_e32 v200, v186, v144
	ds_read_b128 v[186:189], v240 offset:0x100
	s_waitcnt lgkmcnt(3)
	v_exp_f32_e32 v145, v145
	v_mfma_f32_32x32x16_bf16 v[98:113], v[190:193], v[150:153], v[98:113]
	v_add_f32_e32 v241, v230, v129
	ds_read_b128 v[190:193], v240 offset:0x3100
	v_add_f32_e32 v242, v200, v145
	global_load_lds_dwordx4 v214, s[74:75]
	s_waitcnt lgkmcnt(3)
	s_add_i32 m0, s3, 0x2000
	v_mfma_f32_32x32x16_bf16 v[82:97], v[182:185], v[146:149], v[82:97]
	ds_read_b128 v[200:203], v239 offset:0x100
	v_cvt_pk_bf16_f32 v182, v114, v115
	v_cvt_pk_bf16_f32 v184, v118, v119
	s_cmp_le_i32 s23, s9
	v_permlane32_swap_b32_e32 v182, v184
	s_waitcnt lgkmcnt(3)
	s_cselect_b64 s[28:29], -1, 0
	v_mfma_f32_32x32x16_bf16 v[98:113], v[194:197], v[146:149], v[98:113]
	ds_read_b128 v[194:197], v239 offset:0x3100
	v_cvt_pk_bf16_f32 v183, v116, v117
	v_cvt_pk_bf16_f32 v185, v120, v121
	s_cmp_gt_i32 s25, s11
	v_permlane32_swap_b32_e32 v183, v185
	s_waitcnt lgkmcnt(3)
	s_cselect_b64 s[30:31], -1, 0
	v_mfma_f32_32x32x16_bf16 v[82:97], v[186:189], v[10:13], v[82:97]
	ds_read_b128 v[230:233], v238 offset:0x100
	v_cvt_pk_bf16_f32 v186, v122, v123
	v_cvt_pk_bf16_f32 v188, v126, v127
	s_and_b64 s[28:29], s[28:29], s[30:31]
	v_permlane32_swap_b32_e32 v186, v188
	s_waitcnt lgkmcnt(3)
	s_and_b64 vcc, exec, s[28:29]
	v_mfma_f32_32x32x16_bf16 v[98:113], v[190:193], v[10:13], v[98:113]
	ds_read_b128 v[218:221], v238 offset:0x3100
	v_cvt_pk_bf16_f32 v187, v124, v125
	v_cvt_pk_bf16_f32 v189, v128, v129
	s_nop 0
	v_permlane32_swap_b32_e32 v187, v189
	s_waitcnt lgkmcnt(3)
	v_cvt_pk_bf16_f32 v190, v130, v131
	v_cvt_pk_bf16_f32 v192, v134, v135
	v_mfma_f32_32x32x16_bf16 v[82:97], v[200:203], v[6:9], v[82:97]
	v_permlane32_swap_b32_e32 v190, v192
	global_load_lds_dwordx4 v216, s[74:75]
	s_waitcnt lgkmcnt(2)
	v_cvt_pk_bf16_f32 v191, v132, v133
	v_cvt_pk_bf16_f32 v193, v136, v137
	s_nop 0
	v_mfma_f32_32x32x16_bf16 v[98:113], v[194:197], v[6:9], v[98:113]
	v_permlane32_swap_b32_e32 v191, v193
	s_waitcnt lgkmcnt(1)
	v_cvt_pk_bf16_f32 v194, v138, v139
	v_cvt_pk_bf16_f32 v196, v142, v143
	v_mfma_f32_32x32x16_bf16 v[82:97], v[230:233], v[2:5], v[82:97]
	v_permlane32_swap_b32_e32 v194, v196
	s_waitcnt lgkmcnt(0)
	v_cvt_pk_bf16_f32 v195, v140, v141
	v_cvt_pk_bf16_f32 v197, v144, v145
	v_mfma_f32_32x32x16_bf16 v[98:113], v[218:221], v[2:5], v[98:113]
	v_permlane32_swap_b32_e32 v195, v197
	v_add_f32_e32 v115, v241, v242
	v_mov_b32_e32 v116, v115
	s_nop 1
	v_permlane32_swap_b32_e32 v115, v116
	s_cbranch_vccnz .LBB0_2199
	v_add_u32_e32 v114, 59, v237
	v_cmp_gt_u32_e32 vcc, 2.0, v114
	v_add_u32_e32 v114, 27, v237
	s_nop 0
	v_cndmask_b32_e32 v82, v16, v82, vcc
	v_cmp_gt_u32_e32 vcc, 2.0, v114
	v_add_u32_e32 v114, 58, v237
	s_nop 0
	v_cndmask_b32_e32 v98, v16, v98, vcc
	v_cmp_gt_u32_e32 vcc, 2.0, v114
	v_add_u32_e32 v114, 26, v237
	s_nop 0
	v_cndmask_b32_e32 v83, v16, v83, vcc
	v_cmp_gt_u32_e32 vcc, 2.0, v114
	v_add_u32_e32 v114, 57, v237
	s_nop 0
	v_cndmask_b32_e32 v99, v16, v99, vcc
	v_cmp_gt_u32_e32 vcc, 2.0, v114
	v_add_u32_e32 v114, 25, v237
	s_nop 0
	v_cndmask_b32_e32 v84, v16, v84, vcc
	v_cmp_gt_u32_e32 vcc, 2.0, v114
	v_add_u32_e32 v114, 56, v237
	s_nop 0
	v_cndmask_b32_e32 v100, v16, v100, vcc
	v_cmp_gt_u32_e32 vcc, 2.0, v114
	v_add_u32_e32 v114, 24, v237
	s_nop 0
	v_cndmask_b32_e32 v85, v16, v85, vcc
	v_cmp_gt_u32_e32 vcc, 2.0, v114
	v_add_u32_e32 v114, 51, v237
	s_nop 0
	v_cndmask_b32_e32 v101, v16, v101, vcc
	v_cmp_gt_u32_e32 vcc, 2.0, v114
	v_add_u32_e32 v114, 19, v237
	s_nop 0
	v_cndmask_b32_e32 v86, v16, v86, vcc
	v_cmp_gt_u32_e32 vcc, 2.0, v114
	v_add_u32_e32 v114, 50, v237
	s_nop 0
	v_cndmask_b32_e32 v102, v16, v102, vcc
	v_cmp_gt_u32_e32 vcc, 2.0, v114
	v_add_u32_e32 v114, 18, v237
	s_nop 0
	v_cndmask_b32_e32 v87, v16, v87, vcc
	v_cmp_gt_u32_e32 vcc, 2.0, v114
	v_add_u32_e32 v114, 49, v237
	s_nop 0
	v_cndmask_b32_e32 v103, v16, v103, vcc
	v_cmp_gt_u32_e32 vcc, 2.0, v114
	v_add_u32_e32 v114, 17, v237
	s_nop 0
	v_cndmask_b32_e32 v88, v16, v88, vcc
	v_cmp_gt_u32_e32 vcc, 2.0, v114
	v_add_u32_e32 v114, 48, v237
	s_nop 0
	v_cndmask_b32_e32 v104, v16, v104, vcc
	v_cmp_gt_u32_e32 vcc, 2.0, v114
	v_add_u32_e32 v114, 16, v237
	s_nop 0
	v_cndmask_b32_e32 v89, v16, v89, vcc
	v_cmp_gt_u32_e32 vcc, 2.0, v114
	v_add_u32_e32 v114, 43, v237
	s_nop 0
	v_cndmask_b32_e32 v105, v16, v105, vcc
	v_cmp_gt_u32_e32 vcc, 2.0, v114
	v_add_u32_e32 v114, 11, v237
	s_nop 0
	v_cndmask_b32_e32 v90, v16, v90, vcc
	v_cmp_gt_u32_e32 vcc, 2.0, v114
	v_add_u32_e32 v114, 42, v237
	s_nop 0
	v_cndmask_b32_e32 v106, v16, v106, vcc
	v_cmp_gt_u32_e32 vcc, 2.0, v114
	v_add_u32_e32 v114, 10, v237
	s_nop 0
	v_cndmask_b32_e32 v91, v16, v91, vcc
	v_cmp_gt_u32_e32 vcc, 2.0, v114
	v_add_u32_e32 v114, 41, v237
	s_nop 0
	v_cndmask_b32_e32 v107, v16, v107, vcc
	v_cmp_gt_u32_e32 vcc, 2.0, v114
	v_add_u32_e32 v114, 9, v237
	s_nop 0
	v_cndmask_b32_e32 v92, v16, v92, vcc
	v_cmp_gt_u32_e32 vcc, 2.0, v114
	v_add_u32_e32 v114, 40, v237
	s_nop 0
	v_cndmask_b32_e32 v108, v16, v108, vcc
	v_cmp_gt_u32_e32 vcc, 2.0, v114
	v_add_u32_e32 v114, 8, v237
	s_nop 0
	v_cndmask_b32_e32 v93, v16, v93, vcc
	v_cmp_gt_u32_e32 vcc, 2.0, v114
	v_add_u32_e32 v114, 35, v237
	s_nop 0
	v_cndmask_b32_e32 v109, v16, v109, vcc
	v_cmp_gt_u32_e32 vcc, 2.0, v114
	v_add_u32_e32 v114, 3, v237
	s_nop 0
	v_cndmask_b32_e32 v94, v16, v94, vcc
	v_cmp_gt_u32_e32 vcc, 2.0, v114
	v_add_u32_e32 v114, 34, v237
	s_nop 0
	v_cndmask_b32_e32 v110, v16, v110, vcc
	v_cmp_gt_u32_e32 vcc, 2.0, v114
	v_add_u32_e32 v114, 2, v237
	s_nop 0
	v_cndmask_b32_e32 v95, v16, v95, vcc
	v_cmp_gt_u32_e32 vcc, 2.0, v114
	v_add_u32_e32 v114, 33, v237
	s_nop 0
	v_cndmask_b32_e32 v111, v16, v111, vcc
	v_cmp_gt_u32_e32 vcc, 2.0, v114
	v_add_u32_e32 v114, 1, v237
	s_nop 0
	v_cndmask_b32_e32 v96, v16, v96, vcc
	v_cmp_gt_u32_e32 vcc, 2.0, v114
	v_add_u32_e32 v114, 32, v237
	s_nop 0
	v_cndmask_b32_e32 v112, v16, v112, vcc
	v_cmp_gt_u32_e32 vcc, 2.0, v114
	s_nop 1
	v_cndmask_b32_e32 v97, v16, v97, vcc
	v_cmp_gt_u32_e32 vcc, 2.0, v237
	s_nop 1
	v_cndmask_b32_e32 v113, v16, v113, vcc
